# inproj 4th-round tiles (Fourier z, feature tile 16) moved into the mix_a phase on WGs 0..95; mix_a items rebalanced; redundant vmcnt(0) after first DMA removed
# baseline (speedup 1.0000x reference)
.LBB0_4:
	v_readlane_b32 s11, v227, 0
	s_lshl_b32 s1, s11, 2
	s_lshl_b32 s20, s76, 2
	s_cmpk_lt_i32 s11, 0x2de0
	v_writelane_b32 v227, s1, 9
	s_cselect_b64 s[2:3], -1, 0
	v_writelane_b32 v227, s2, 10
	s_mul_hi_i32 s1, s11, 0x59493e15
	v_mov_b32_e32 v1, 0xb60
	v_writelane_b32 v227, s3, 11
	s_lshr_b32 s2, s1, 31
	s_ashr_i32 s1, s1, 10
	s_add_i32 s2, s1, s2
	s_mul_i32 s1, s2, 0xfffff488
	s_add_i32 s1, s1, s11
	s_cmpk_gt_i32 s1, 0x21f
	s_cselect_b64 s[6:7], -1, 0
	v_writelane_b32 v227, s6, 12
	s_cmpk_gt_u32 s1, 0x31f
	v_sub_co_u32_e32 v1, vcc, s1, v1
	v_writelane_b32 v227, s7, 13
	s_cselect_b64 s[6:7], -1, 0
	v_writelane_b32 v227, s6, 14
	s_cmpk_gt_u32 s1, 0x89f
	v_mov_b32_e32 v2, 0xb68
	v_writelane_b32 v227, s7, 15
	s_cselect_b64 s[6:7], -1, 0
	v_writelane_b32 v227, s6, 16
	s_mul_i32 s0, s77, s76
	s_movk_i32 s77, 0x3ff
	v_writelane_b32 v227, s7, 17
	s_xor_b64 s[6:7], vcc, -1
	v_writelane_b32 v227, s6, 18
	v_sub_co_u32_e32 v2, vcc, s1, v2
	s_nop 0
	v_writelane_b32 v227, s7, 19
	s_xor_b64 s[6:7], vcc, -1
	v_writelane_b32 v227, s6, 20
	s_cmpk_gt_u32 s1, 0xb6f
	s_mov_b32 s89, 0
	v_writelane_b32 v227, s7, 21
	s_cselect_b64 s[6:7], -1, 0
	v_writelane_b32 v227, s6, 22
	s_ashr_i32 s3, s2, 31
	s_lshl_b32 s5, s1, 5
	v_writelane_b32 v227, s7, 23
	s_lshl_b64 s[6:7], s[2:3], 17
	v_writelane_b32 v227, s6, 24
	s_add_i32 s5, s5, 0x7ffe9200
	s_and_b32 s5, s5, 0x7fffffc0
	v_writelane_b32 v227, s7, 25
	s_lshl_b64 s[6:7], s[2:3], 16
	v_writelane_b32 v227, s6, 26
	s_lshl_b32 s8, s2, 1
	s_mov_b64 s[70:71], 0x1000
	v_writelane_b32 v227, s7, 27
	v_writelane_b32 v227, s5, 28
	s_lshl_b32 s5, s11, 6
	s_and_b32 s6, s5, 64
	v_writelane_b32 v227, s6, 29
	v_readfirstlane_b32 s6, v2
	s_lshr_b32 s6, s6, 2
	s_add_i32 s6, s6, s8
	s_ashr_i32 s7, s6, 31
	s_lshl_b64 s[12:13], s[6:7], 16
	v_writelane_b32 v227, s12, 30
	s_lshl_b64 s[6:7], s[6:7], 15
	s_and_b32 s5, s5, 0xc0
	v_writelane_b32 v227, s13, 31
	v_writelane_b32 v227, s6, 32
	s_mov_b64 s[74:75], 0x1200
	v_mov_b32_e32 v154, 0x358637bd
	v_writelane_b32 v227, s7, 33
	v_writelane_b32 v227, s5, 34
	v_readfirstlane_b32 s5, v1
	s_lshr_b32 s5, s5, 2
	s_add_i32 s6, s5, s8
	s_ashr_i32 s7, s6, 31
	s_lshl_b64 s[8:9], s[6:7], 16
	v_writelane_b32 v227, s8, 35
	s_lshl_b64 s[6:7], s[6:7], 15
	s_mul_hi_i32 s5, s2, 0xb00000
	v_writelane_b32 v227, s9, 36
	v_writelane_b32 v227, s6, 37
	v_mov_b32_e32 v1, 0x100
	v_sub_co_u32_e32 v1, vcc, s11, v1
	v_writelane_b32 v227, s7, 38
	v_writelane_b32 v227, s5, 39
	s_mul_i32 s5, s2, 0xb00000
	v_writelane_b32 v227, s5, 40
	s_mul_hi_i32 s5, s2, 0x580000
	v_writelane_b32 v227, s5, 41
	s_mul_i32 s5, s2, 0x580000
	v_writelane_b32 v227, s5, 42
	s_add_i32 s5, s1, 0xf760
	s_and_b32 s6, s5, 0xffff
	s_mul_i32 s6, s6, 0xba2f
	s_lshr_b32 s6, s6, 21
	s_lshl_b32 s7, s6, 6
	s_mul_i32 s6, s6, 44
	s_sub_i32 s5, s5, s6
	s_lshl_b32 s5, s5, 6
	v_writelane_b32 v227, s7, 43
	s_and_b32 s5, s5, 0xffc0
	v_writelane_b32 v227, s5, 44
	s_mul_hi_i32 s5, s2, 0x1600000
	v_writelane_b32 v227, s5, 45
	s_mul_i32 s5, s2, 0x1600000
	v_writelane_b32 v227, s5, 46
	s_lshl_b32 s5, s1, 2
	s_add_i32 s6, s5, 0x7ffff380
	s_and_b32 s6, s6, 0x7fffffc0
	v_writelane_b32 v227, s6, 47
	s_lshl_b32 s6, s1, 6
	s_and_b32 s6, s6, 0x3c0
	v_writelane_b32 v227, s6, 48
	s_lshl_b64 s[6:7], s[2:3], 20
	v_writelane_b32 v227, s6, 49
	s_add_i32 s5, s5, 0x7ffff780
	s_and_b32 s3, s5, 0x7fffffc0
	v_writelane_b32 v227, s7, 50
	v_writelane_b32 v227, s3, 51
	s_mul_hi_i32 s3, s2, 0x880000
	v_writelane_b32 v227, s3, 52
	s_mul_i32 s3, s2, 0x880000
	v_writelane_b32 v227, s3, 53
	s_mul_hi_i32 s3, s2, 0x440000
	v_writelane_b32 v227, s3, 54
	s_mul_i32 s2, s2, 0x440000
	v_writelane_b32 v227, s2, 55
	s_ashr_i32 s2, s1, 31
	s_lshr_b32 s2, s2, 28
	s_add_i32 s2, s1, s2
	s_lshl_b32 s3, s2, 2
	s_and_b32 s2, s2, 0x3fffff0
	s_sub_i32 s1, s1, s2
	s_andn2_b32 s3, s3, 63
	s_lshl_b32 s1, s1, 6
	v_writelane_b32 v227, s3, 56
	s_cmpk_lt_i32 s11, 0x180
	v_writelane_b32 v227, s1, 57
	s_cselect_b64 s[2:3], -1, 0
	s_lshl_b32 s12, s11, 8
	s_lshl_b32 s13, s76, 8
	s_lshr_b32 s14, s11, 3
	v_writelane_b32 v227, s2, 58
	s_cmpk_lt_u32 s11, 0xb00
	s_mov_b32 s26, s13
	v_writelane_b32 v227, s3, 59
	s_cselect_b64 s[2:3], -1, 0
	s_lshl_b32 s1, s11, 3
	v_writelane_b32 v227, s2, 60
	s_and_b32 s30, s1, 56
	s_bfe_u32 s1, s11, 0x30003
	v_writelane_b32 v227, s3, 61
	s_or_b32 s1, s1, s30
	v_writelane_b32 v227, s1, 62
	s_lshr_b32 s1, s11, 6
	v_writelane_b32 v227, s1, 63
	s_lshr_b32 s1, s76, 3
	s_cmpk_lt_u32 s11, 0x200
	v_writelane_b32 v226, s1, 0
	s_cselect_b64 s[2:3], -1, 0
	v_writelane_b32 v226, s2, 1
	s_cmpk_gt_i32 s11, 0x7f
	s_mov_b32 s88, 0x800000
	v_writelane_b32 v226, s3, 2
	s_cselect_b64 s[2:3], -1, 0
	v_writelane_b32 v226, s2, 3
	s_add_i32 s15, s76, 0xffffff80
	s_add_i32 s1, s11, 0xffffff80
	s_and_b32 s5, s11, 0x7fffff80
	v_writelane_b32 v226, s3, 4
	s_and_b64 s[2:3], vcc, exec
	s_cselect_b32 s6, s11, s1
	s_cmpk_lg_i32 s5, 0x100
	s_cselect_b64 s[2:3], -1, 0
	s_cmpk_eq_i32 s5, 0x100
	v_readfirstlane_b32 s5, v1
	s_cselect_b32 s10, s5, s6
	s_cmpk_lg_i32 s76, 0x200
	s_cselect_b64 s[6:7], -1, 0
	s_and_b64 s[8:9], s[6:7], exec
	v_writelane_b32 v226, s15, 5
	s_cselect_b32 s31, s15, 0x180
	s_cselect_b32 s10, s1, s10
	s_mov_b64 s[2:3], -1
	v_writelane_b32 v226, s2, 6
	s_cmpk_lt_i32 s11, 0x100
	v_lshrrev_b32_e32 v1, 20, v0
	v_writelane_b32 v226, s3, 7
	s_cselect_b64 s[2:3], -1, 0
	s_or_b64 s[2:3], s[2:3], s[6:7]
	s_and_b64 s[2:3], s[2:3], exec
	s_cselect_b32 s15, s11, s1
	s_cmpk_lt_u32 s5, 0x80
	s_cselect_b32 s15, s5, s15
	s_cmpk_lt_i32 s15, 0x200
	s_cselect_b64 s[2:3], -1, 0
	s_lshr_b32 s1, s31, 31
	s_add_i32 s1, s31, s1
	s_ashr_i32 s1, s1, 1
	s_movk_i32 s1, 0x100
	s_add_i32 s6, s15, s1
	v_writelane_b32 v226, s2, 8
	s_cmpk_lt_i32 s15, 0x100
	v_lshrrev_b32_e32 v0, 10, v0
	v_writelane_b32 v226, s3, 9
	s_cselect_b64 s[2:3], -1, 0
	v_writelane_b32 v226, s2, 10
	s_cmpk_lt_i32 s15, 0x80
	v_or_b32_e32 v0, v0, v1
	v_writelane_b32 v226, s3, 11
	s_cselect_b64 s[2:3], -1, 0
	v_writelane_b32 v226, s2, 12
	s_bfe_i32 s1, s11, 0x10000
	s_and_b32 s7, s11, 1
	v_writelane_b32 v226, s3, 13
	s_ashr_i32 s2, s11, 5
	s_lshl_b32 s5, s2, 11
	s_and_b32 s3, s1, 0x7ff
	s_lshl_b32 s1, s11, 1
	v_writelane_b32 v226, s5, 14
	s_and_b32 s1, s1, 48
	s_bfe_u32 s8, s11, 0x20001
	s_or_b32 s5, s5, s3
	v_writelane_b32 v226, s1, 15
	s_lshl_b32 s1, s2, 2
	s_cmp_eq_u32 s7, 0
	s_cselect_b32 s16, 1, -1
	v_writelane_b32 v226, s1, 16
	s_mul_i32 s2, s16, 0x300
	v_writelane_b32 v226, s2, 17
	s_mul_i32 s2, s7, 0x900000
	s_mul_i32 s9, s8, 0xc0
	s_or_b32 s2, s2, s9
	v_writelane_b32 v226, s9, 18
	s_addk_i32 s2, 0xff40
	v_writelane_b32 v226, s2, 19
	s_add_i32 s42, s5, 0x1000
	s_mul_i32 s2, s7, 0xc00000
	v_writelane_b32 v226, s2, 20
	s_mul_i32 s5, s42, 0x300
	s_lshl_b32 s83, s16, 3
	v_writelane_b32 v226, s5, 21
	s_add_i32 s5, s83, s42
	s_mul_i32 s9, s5, 0x300
	s_add_i32 s5, s5, s83
	v_writelane_b32 v226, s9, 22
	s_mul_i32 s9, s5, 0x300
	s_add_i32 s5, s5, s83
	v_writelane_b32 v226, s9, 23
	s_mul_i32 s9, s5, 0x300
	s_add_i32 s5, s5, s83
	v_writelane_b32 v226, s9, 24
	s_mulk_i32 s5, 0x300
	s_lshl_b32 s2, s8, 6
	v_writelane_b32 v226, s5, 25
	s_add_i32 s5, s76, s11
	s_cmpk_lt_i32 s11, 0x300
	s_cselect_b64 s[18:19], -1, 0
	v_writelane_b32 v226, s18, 26
	s_cmpk_lt_u32 s11, 0x660
	v_and_or_b32 v0, v0, s77, v131
	v_writelane_b32 v226, s19, 27
	s_cselect_b64 s[18:19], -1, 0
	s_and_b32 s9, s11, 7
	v_writelane_b32 v226, s18, 28
	s_mul_i32 s17, s9, 12
	s_mul_i32 s9, s14, 0xab
	v_writelane_b32 v226, s19, 29
	s_bfe_u32 s9, s9, 0x5000b
	v_writelane_b32 v226, s9, 30
	s_mul_i32 s9, s9, 12
	s_sub_i32 s9, s14, s9
	s_and_b32 s9, s9, 0xff
	v_writelane_b32 v226, s14, 31
	s_add_i32 s9, s17, s9
	v_writelane_b32 v226, s17, 32
	s_cmp_lt_i32 s78, 0
	v_writelane_b32 v226, s9, 33
	s_cselect_b64 s[18:19], -1, 0
	v_writelane_b32 v226, s18, 34
	s_mov_b32 s1, -1
	s_movk_i32 s81, 0x6000
	v_writelane_b32 v226, s19, 35
	v_cmp_eq_u32_e64 s[18:19], 0, v0
	v_cvt_f32_u32_e32 v0, s13
	s_mov_b64 s[24:25], 0x80
	v_writelane_b32 v226, s18, 36
	s_mov_b64 s[36:37], 0x100
	v_rcp_iflag_f32_e32 v0, v0
	v_writelane_b32 v226, s19, 37
	v_readlane_b32 s18, v227, 7
	v_readlane_b32 s19, v227, 8
	s_load_dword s9, s[18:19], 0x230
	s_load_dwordx2 s[22:23], s[18:19], 0x1f8
	v_mul_f32_e32 v0, 0x4f7ffffe, v0
	v_cvt_u32_f32_e32 v0, v0
	s_mov_b64 s[62:63], 0x10080
	s_waitcnt lgkmcnt(0)
	s_mul_i32 s91, s0, s9
	s_add_u32 s40, s22, 0x200
	s_addc_u32 s41, s23, 0
	s_add_u32 s64, s22, 0x1000
	s_addc_u32 s65, s23, 0
	s_add_u32 s38, s22, 0x1100
	s_addc_u32 s39, s23, 0
	s_add_u32 s54, s22, 0x1200
	s_addc_u32 s55, s23, 0
	s_add_u32 s18, s22, 0x1300
	s_addc_u32 s19, s23, 0
	v_writelane_b32 v226, s18, 38
	s_cmp_eq_u32 s4, 15
	s_mov_b64 s[34:35], 0x20080
	v_writelane_b32 v226, s19, 39
	s_cselect_b64 s[18:19], -1, 0
	v_writelane_b32 v226, s18, 40
	s_cmp_eq_u32 s4, 14
	s_mov_b64 s[94:95], 0x30080
	v_writelane_b32 v226, s19, 41
	s_cselect_b64 s[18:19], -1, 0
	v_writelane_b32 v226, s18, 42
	s_cmp_eq_u32 s4, 13
	s_mov_b64 s[96:97], 0x20100
	v_writelane_b32 v226, s19, 43
	s_cselect_b64 s[18:19], -1, 0
	v_writelane_b32 v226, s18, 44
	s_cmp_eq_u32 s4, 12
	s_mov_b64 s[86:87], 0x30100
	v_writelane_b32 v226, s19, 45
	s_cselect_b64 s[18:19], -1, 0
	v_writelane_b32 v226, s18, 46
	s_cmp_eq_u32 s4, 11
	s_mov_b64 s[68:69], 0x40100
	v_writelane_b32 v226, s19, 47
	s_cselect_b64 s[18:19], -1, 0
	v_writelane_b32 v226, s18, 48
	s_cmp_eq_u32 s4, 10
	v_mov_b32_e32 v155, 0x3a27c5ac
	v_writelane_b32 v226, s19, 49
	s_cselect_b64 s[18:19], -1, 0
	v_writelane_b32 v226, s18, 50
	s_cmp_eq_u32 s4, 9
	s_movk_i32 s17, 0xc00
	v_writelane_b32 v226, s19, 51
	s_cselect_b64 s[18:19], -1, 0
	v_writelane_b32 v226, s18, 52
	s_cmp_eq_u32 s4, 8
	s_movk_i32 s82, 0xfefe
	v_writelane_b32 v226, s19, 53
	s_cselect_b64 s[18:19], -1, 0
	v_writelane_b32 v226, s18, 54
	s_cmp_eq_u32 s4, 7
	v_mov_b32_e32 v156, 0x3ca908c9
	v_writelane_b32 v226, s19, 55
	s_cselect_b64 s[18:19], -1, 0
	v_writelane_b32 v226, s18, 56
	s_cmp_eq_u32 s4, 6
	v_mov_b32_e32 v157, 0xbf1f24be
	v_writelane_b32 v226, s19, 57
	s_cselect_b64 s[18:19], -1, 0
	v_writelane_b32 v226, s18, 58
	s_cmp_eq_u32 s4, 5
	v_mov_b32_e32 v158, 0x3e642e9d
	v_writelane_b32 v226, s19, 59
	s_cselect_b64 s[18:19], -1, 0
	v_writelane_b32 v226, s18, 60
	s_cmp_eq_u32 s4, 4
	v_mov_b32_e32 v159, 0x3e91f4c4
	v_writelane_b32 v226, s19, 61
	s_cselect_b64 s[18:19], -1, 0
	v_writelane_b32 v226, s18, 62
	s_cmp_eq_u32 s4, 3
	v_mov_b32_e32 v160, 0x3c0881c4
	v_writelane_b32 v226, s19, 63
	s_cselect_b64 s[18:19], -1, 0
	v_writelane_b32 v225, s18, 0
	s_cmp_eq_u32 s4, 2
	v_mov_b32_e32 v161, 0xbab64f3b
	v_writelane_b32 v225, s19, 1
	s_cselect_b64 s[18:19], -1, 0
	v_writelane_b32 v225, s18, 2
	s_cmp_eq_u32 s4, 1
	s_mov_b32 s80, 0xfffff
	v_writelane_b32 v225, s19, 3
	s_cselect_b64 s[18:19], -1, 0
	v_writelane_b32 v225, s18, 4
	s_cmp_eq_u32 s4, 0
	s_mov_b32 s90, 0x300000
	v_writelane_b32 v225, s19, 5
	s_cselect_b64 s[18:19], -1, 0
	s_lshl_b32 s0, s4, 8
	s_add_u32 s0, s22, s0
	v_writelane_b32 v225, s18, 6
	s_addc_u32 s4, s23, 0
	v_mov_b32_e32 v162, 1
	v_writelane_b32 v225, s19, 7
	s_add_u32 s18, s0, 0x1400
	s_addc_u32 s19, s4, 0
	v_writelane_b32 v225, s18, 8
	v_mov_b32_e32 v163, 0x60
	v_mov_b32_e32 v164, 0x3b3504f3
	v_writelane_b32 v225, s19, 9
	s_add_u32 s18, s0, 0x2400
	s_addc_u32 s19, s4, 0
	v_writelane_b32 v225, s18, 10
	v_bfrev_b32_e32 v165, 60
	v_mov_b32_e32 v166, 0xf149f2ca
	v_writelane_b32 v225, s19, 11
	s_add_u32 s18, s22, 0x3400
	s_addc_u32 s19, s23, 0
	v_writelane_b32 v225, s18, 12
	v_mov_b32_e32 v167, 0x7fc
	v_bfrev_b32_e32 v168, 0.5
	v_writelane_b32 v225, s19, 13
	s_add_u32 s18, s22, 0x3500
	s_addc_u32 s19, s23, 0
	v_writelane_b32 v225, s18, 14
	s_cmpk_lt_u32 s10, 0x200
	s_mov_b64 s[22:23], 0x40080
	v_writelane_b32 v225, s19, 15
	v_writelane_b32 v225, s10, 16
	s_cselect_b64 s[18:19], -1, 0
	v_writelane_b32 v225, s18, 17
	s_lshl_b32 s0, s7, 16
	s_lshl_b32 s4, s8, 14
	v_writelane_b32 v225, s19, 18
	s_or_b32 s0, s0, s4
	v_writelane_b32 v225, s0, 19
	v_writelane_b32 v225, s12, 20
	s_add_i32 s0, s12, s13
	v_writelane_b32 v225, s0, 21
	s_lshl_b32 s0, s76, 10
	v_writelane_b32 v225, s0, 22
	v_writelane_b32 v225, s0, 23
	v_writelane_b32 v225, s0, 24
	v_writelane_b32 v225, s0, 25
	s_mov_b32 s12, s13
	s_mov_b32 s0, s89
	s_and_b64 s[0:1], s[12:13], s[0:1]
	v_writelane_b32 v225, s0, 26
	s_abs_i32 s4, s31
	s_lshl_b32 s33, s76, 9
	v_writelane_b32 v225, s1, 27
	s_sub_i32 s0, 0, s13
	v_mul_lo_u32 v1, s0, v0
	v_mul_hi_u32 v1, v0, v1
	v_add_u32_e32 v133, v0, v1
	v_cvt_f32_u32_e32 v0, s4
	v_writelane_b32 v225, s33, 28
	v_writelane_b32 v225, s33, 29
	s_mov_b32 s1, s13
	v_rcp_iflag_f32_e32 v0, v0
	v_writelane_b32 v225, s0, 30
	s_ashr_i32 s27, s13, 31
	v_mov_b32_e32 v1, 0
	v_mul_f32_e32 v0, 0x4f7ffffe, v0
	v_cvt_u32_f32_e32 v0, v0
	v_writelane_b32 v225, s1, 31
	s_ashr_i32 s0, s6, 31
	s_abs_i32 s1, s6
	s_sub_i32 s6, 0, s4
	v_readfirstlane_b32 s7, v0
	s_mul_i32 s6, s6, s7
	s_mul_hi_u32 s6, s7, s6
	s_add_i32 s7, s7, s6
	s_mul_hi_u32 s6, s1, s7
	s_mul_i32 s6, s6, s4
	v_cvt_f32_u32_e32 v0, s76
	s_sub_i32 s1, s1, s6
	s_sub_i32 s6, s1, s4
	s_cmp_ge_u32 s1, s4
	s_cselect_b32 s1, s6, s1
	v_rcp_iflag_f32_e32 v0, v0
	s_sub_i32 s6, s1, s4
	s_cmp_ge_u32 s1, s4
	s_cselect_b32 s1, s6, s1
	s_xor_b32 s1, s1, s0
	v_mul_f32_e32 v0, 0x4f7ffffe, v0
	s_sub_i32 s10, s1, s0
	v_cvt_u32_f32_e32 v0, v0
	s_cmpk_lt_i32 s10, 0x100
	s_cselect_b64 s[6:7], -1, 0
	v_writelane_b32 v225, s6, 32
	s_sub_i32 s4, 0, s76
	s_mov_b64 s[18:19], 0x50080
	v_writelane_b32 v225, s7, 33
	v_readfirstlane_b32 s6, v0
	s_mul_i32 s4, s4, s6
	s_mul_hi_u32 s4, s6, s4
	s_add_i32 s6, s6, s4
	s_mul_hi_u32 s4, s5, s6
	s_mul_i32 s4, s4, s76
	s_sub_i32 s4, s5, s4
	s_sub_i32 s7, s4, s76
	s_cmp_ge_u32 s4, s76
	s_cselect_b32 s4, s7, s4
	s_sub_i32 s7, s4, s76
	s_cmp_ge_u32 s4, s76
	s_cselect_b32 s4, s7, s4
	s_cmpk_lt_i32 s4, 0xc0
	v_writelane_b32 v225, s4, 34
	s_cselect_b64 s[8:9], -1, 0
	s_abs_i32 s4, s76
	v_cvt_f32_u32_e32 v0, s4
	v_writelane_b32 v225, s8, 35
	s_sub_i32 s7, 0, s4
	v_mov_b32_e32 v169, 0x7f800000
	v_rcp_iflag_f32_e32 v0, v0
	v_writelane_b32 v225, s9, 36
	v_mov_b32_e32 v170, 0x1000
	v_mov_b32_e32 v171, 0xfffff800
	v_mul_f32_e32 v0, 0x4f7ffffe, v0
	v_cvt_u32_f32_e32 v0, v0
	v_mov_b32_e32 v172, 0xffffff00
	v_mov_b32_e32 v173, 0x1800000
	v_mov_b32_e32 v174, 0xffc00000
	v_readfirstlane_b32 s8, v0
	s_mul_i32 s7, s7, s8
	s_mul_hi_u32 s7, s8, s7
	s_add_i32 s8, s8, s7
	s_mul_hi_u32 s7, s8, 0xc0
	s_mul_i32 s7, s7, s4
	s_sub_i32 s7, 0xc0, s7
	s_sub_i32 s9, s7, s4
	s_cmp_ge_u32 s7, s4
	s_cselect_b32 s7, s9, s7
	s_sub_i32 s9, s7, s4
	s_cmp_ge_u32 s7, s4
	s_cselect_b32 s7, s9, s7
	s_sub_i32 s7, s5, s7
	s_mul_hi_u32 s9, s7, s6
	s_mul_i32 s9, s9, s76
	s_sub_i32 s7, s7, s9
	s_sub_i32 s9, s7, s76
	s_cmp_ge_u32 s7, s76
	s_cselect_b32 s7, s9, s7
	s_sub_i32 s9, s7, s76
	s_cmp_ge_u32 s7, s76
	s_cselect_b32 s7, s9, s7
	v_writelane_b32 v225, s7, 37
	s_cmpk_lt_i32 s7, 0xc0
	s_mul_hi_u32 s7, s8, 0x180
	s_mul_i32 s7, s7, s4
	s_cselect_b64 s[12:13], -1, 0
	s_sub_i32 s7, 0x180, s7
	s_sub_i32 s9, s7, s4
	s_cmp_ge_u32 s7, s4
	s_cselect_b32 s7, s9, s7
	s_sub_i32 s9, s7, s4
	s_cmp_ge_u32 s7, s4
	s_cselect_b32 s7, s9, s7
	s_sub_i32 s7, s5, s7
	s_mul_hi_u32 s9, s7, s6
	s_mul_i32 s9, s9, s76
	s_sub_i32 s7, s7, s9
	s_sub_i32 s9, s7, s76
	s_cmp_ge_u32 s7, s76
	s_cselect_b32 s7, s9, s7
	s_sub_i32 s9, s7, s76
	v_writelane_b32 v225, s12, 38
	s_cmp_ge_u32 s7, s76
	s_cselect_b32 s7, s9, s7
	v_writelane_b32 v225, s13, 39
	v_writelane_b32 v225, s7, 40
	s_cmpk_lt_i32 s7, 0xc0
	s_mul_hi_u32 s7, s8, 0x240
	s_mul_i32 s7, s7, s4
	s_cselect_b64 s[12:13], -1, 0
	s_sub_i32 s7, 0x240, s7
	s_sub_i32 s9, s7, s4
	s_cmp_ge_u32 s7, s4
	s_cselect_b32 s7, s9, s7
	s_sub_i32 s9, s7, s4
	s_cmp_ge_u32 s7, s4
	s_cselect_b32 s7, s9, s7
	s_sub_i32 s7, s5, s7
	s_mul_hi_u32 s9, s7, s6
	s_mul_i32 s9, s9, s76
	s_sub_i32 s7, s7, s9
	s_sub_i32 s9, s7, s76
	s_cmp_ge_u32 s7, s76
	s_cselect_b32 s7, s9, s7
	s_sub_i32 s9, s7, s76
	v_writelane_b32 v225, s12, 41
	s_cmp_ge_u32 s7, s76
	s_cselect_b32 s7, s9, s7
	v_writelane_b32 v225, s13, 42
	v_writelane_b32 v225, s7, 43
	s_cmpk_lt_i32 s7, 0xc0
	s_mul_hi_u32 s7, s8, 0x300
	s_mul_i32 s7, s7, s4
	s_cselect_b64 s[12:13], -1, 0
	s_sub_i32 s7, 0x300, s7
	s_sub_i32 s8, s7, s4
	s_cmp_ge_u32 s7, s4
	s_cselect_b32 s7, s8, s7
	s_sub_i32 s8, s7, s4
	s_cmp_ge_u32 s7, s4
	s_cselect_b32 s4, s8, s7
	s_sub_i32 s4, s5, s4
	s_mul_hi_u32 s6, s4, s6
	s_mul_i32 s6, s6, s76
	s_sub_i32 s4, s4, s6
	s_sub_i32 s6, s4, s76
	s_cmp_ge_u32 s4, s76
	s_cselect_b32 s4, s6, s4
	s_sub_i32 s6, s4, s76
	s_cmp_ge_u32 s4, s76
	v_writelane_b32 v225, s12, 44
	s_cselect_b32 s4, s6, s4
	s_cmpk_lt_i32 s4, 0xc0
	v_writelane_b32 v225, s13, 45
	v_writelane_b32 v225, s4, 46
	s_cselect_b64 s[6:7], -1, 0
	v_writelane_b32 v225, s6, 47
	s_lshl_b32 s4, s5, 5
	s_add_i32 s4, s4, 0x7ffe9200
	v_writelane_b32 v225, s7, 48
	v_writelane_b32 v225, s4, 49
	s_lshl_b32 s4, s76, 5
	v_writelane_b32 v225, s4, 50
	s_lshl_b32 s4, s5, 2
	s_add_i32 s4, s4, 0x7ffff380
	v_writelane_b32 v225, s4, 51
	s_lshl_b32 s4, s5, 6
	v_writelane_b32 v225, s4, 52
	s_lshl_b32 s4, s76, 6
	v_writelane_b32 v225, s4, 53
	s_lshl_b64 s[4:5], s[26:27], 2
	v_writelane_b32 v225, s4, 54
	s_lshl_b64 s[28:29], s[26:27], 1
	v_mbcnt_lo_u32_b32 v0, -1, 0
	v_writelane_b32 v225, s5, 55
	s_lshl_b32 s4, s11, 18
	v_writelane_b32 v225, s4, 56
	s_lshl_b32 s4, s76, 20
	s_bitcmp1_b32 s15, 0
	v_writelane_b32 v225, s4, 57
	s_cselect_b64 s[4:5], -1, 0
	v_writelane_b32 v225, s4, 58
	s_bitcmp1_b32 s31, 0
	v_mbcnt_hi_u32_b32 v150, -1, v0
	v_writelane_b32 v225, s5, 59
	s_cselect_b64 s[4:5], -1, 0
	v_writelane_b32 v225, s4, 60
	s_bitcmp1_b32 s10, 0
	v_and_b32_e32 v0, 64, v150
	v_writelane_b32 v225, s5, 61
	v_writelane_b32 v225, s10, 62
	s_cselect_b64 s[4:5], -1, 0
	s_lshl_b32 s1, s1, 5
	s_lshl_b32 s0, s0, 5
	v_writelane_b32 v225, s4, 63
	s_sub_i32 s0, s1, s0
	s_ashr_i32 s21, s20, 31
	v_writelane_b32 v224, s5, 0
	v_writelane_b32 v224, 0, 40
	v_writelane_b32 v224, s0, 1
	s_lshl_b32 s0, s31, 5
	v_writelane_b32 v224, s0, 2
	v_writelane_b32 v224, s15, 3
	s_lshl_b32 s0, s15, 5
	v_writelane_b32 v224, s0, 4
	s_or_b32 s0, s3, 0x1000
	v_writelane_b32 v224, s0, 5
	v_writelane_b32 v224, s16, 6
	s_lshl_b32 s0, s16, 5
	v_writelane_b32 v224, s0, 7
	s_lshl_b32 s0, s11, 4
	v_writelane_b32 v224, s0, 8
	s_lshl_b32 s0, s76, 4
	v_writelane_b32 v224, s0, 9
	s_lshl_b64 s[0:1], s[20:21], 2
	v_writelane_b32 v224, s0, 10
	v_xor_b32_e32 v151, 16, v150
	v_add_u32_e32 v152, 64, v0
	v_writelane_b32 v224, s1, 11
	s_lshl_b64 s[0:1], s[20:21], 12
	v_writelane_b32 v224, s0, 12
	v_xor_b32_e32 v153, 32, v150
	s_mov_b64 s[10:11], 0x10100
	v_writelane_b32 v224, s1, 13
	s_mov_b32 s0, s20
	v_writelane_b32 v224, s0, 14
	s_mov_b32 s5, 0x100000
	v_mov_b32_e32 v175, 0x7fc00000
	v_writelane_b32 v224, s1, 15
	s_lshl_b64 s[0:1], s[20:21], 11
	v_writelane_b32 v224, s0, 16
	v_mov_b32_e32 v176, 0x461c4000
	v_mov_b32_e32 v177, 0x37000000
	v_writelane_b32 v224, s1, 17
	s_lshl_b32 s0, s2, 2
	v_writelane_b32 v224, s0, 18
	v_writelane_b32 v224, s30, 19
	v_writelane_b32 v224, s31, 20
	v_writelane_b32 v224, s42, 21
	v_writelane_b32 v224, s83, 22
	v_writelane_b32 v224, s91, 23
	v_writelane_b32 v224, s40, 24
	s_mov_b32 s0, 0x7f800000
	s_mov_b32 s1, 0x18000
	v_writelane_b32 v224, s41, 25
	v_writelane_b32 v224, s64, 26
	v_not_b32_e32 v178, 63
	v_not_b32_e32 v179, 31
	v_writelane_b32 v224, s65, 27
	v_writelane_b32 v224, s54, 28
	v_mov_b32_e32 v130, v1
	v_mov_b32_e32 v132, v1
	v_writelane_b32 v224, s55, 29
	v_writelane_b32 v224, s38, 30
	s_mov_b32 s31, s42
	s_nop 0
	v_writelane_b32 v224, s39, 31
	v_writelane_b32 v224, s28, 32
	s_nop 1
	v_writelane_b32 v224, s29, 33
	s_branch .LBB0_7

.LBB0_38:
	s_mul_i32 s2, s61, 0xb0000
	s_waitcnt lgkmcnt(0)
	v_mov_b32_e32 v2, v131
	s_mul_hi_u32 s3, s61, 0xb0000
	s_add_u32 s2, s16, s2
	s_mul_i32 s88, s60, 0x84000
	s_addc_u32 s3, s56, s3
	v_lshrrev_b32_e32 v0, 4, v2
	s_lshl_b64 s[42:43], s[88:89], 1
	v_ashrrev_i32_e32 v3, 3, v2
	v_xor_b32_e32 v0, v0, v2
	s_movk_i32 s58, 0xb00
	s_add_u32 s42, s44, s42
	v_mad_i64_i32 v[4:5], s[58:59], v3, s58, 0
	v_lshlrev_b32_e32 v3, 3, v0
	s_addc_u32 s43, s45, s43
	v_lshlrev_b64 v[100:101], 1, v[4:5]
	v_and_b32_e32 v3, 56, v3
	v_lshlrev_b32_e32 v124, 4, v2
	v_lshl_add_u64 v[102:103], s[2:3], 0, v[100:101]
	v_lshl_add_u64 v[104:105], s[42:43], 0, v[100:101]
	s_and_b64 vcc, exec, s[20:21]
	v_add_u32_e32 v123, 0x1000, v124
	v_add_u32_e32 v122, 0x2000, v124
	v_add_u32_e32 v121, 0x3000, v124
	v_add_u32_e32 v120, 0x4000, v124
	v_add_u32_e32 v119, 0x5000, v124
	v_add_u32_e32 v118, 0x6000, v124
	v_add_u32_e32 v117, 0x7000, v124
	v_add_u32_e32 v111, 0x8000, v124
	v_add_u32_e32 v110, 0x9000, v124
	v_lshlrev_b32_e32 v98, 1, v3
	s_cbranch_vccnz .LBB0_40
	v_mov_b32_e32 v99, v1
	v_readfirstlane_b32 s2, v124
	v_lshl_add_u64 v[4:5], v[102:103], 0, v[98:99]
	s_mov_b32 m0, s2
	s_mov_b64 s[20:21], 0x2c000
	v_readfirstlane_b32 s2, v123
	global_load_lds_dwordx4 v[4:5], off
	v_lshl_add_u64 v[8:9], v[4:5], 0, s[20:21]
	s_mov_b32 m0, s2
	s_mov_b64 s[42:43], 0x58000
	v_readfirstlane_b32 s2, v122
	global_load_lds_dwordx4 v[8:9], off
	v_lshl_add_u64 v[8:9], v[4:5], 0, s[42:43]
	s_mov_b32 m0, s2
	s_mov_b64 s[58:59], 0x84000
	v_readfirstlane_b32 s2, v121
	global_load_lds_dwordx4 v[8:9], off
	v_lshl_add_u64 v[4:5], v[4:5], 0, s[58:59]
	s_mov_b32 m0, s2
	v_readfirstlane_b32 s2, v120
	v_lshl_add_u64 v[6:7], v[104:105], 0, v[98:99]
	global_load_lds_dwordx4 v[4:5], off
	s_mov_b32 m0, s2
	v_readfirstlane_b32 s2, v119
	global_load_lds_dwordx4 v[6:7], off
	v_lshl_add_u64 v[4:5], v[6:7], 0, s[20:21]
	s_mov_b32 m0, s2
	v_readfirstlane_b32 s2, v118
	global_load_lds_dwordx4 v[4:5], off
	v_lshl_add_u64 v[4:5], v[6:7], 0, s[42:43]
	s_mov_b32 m0, s2
	v_readfirstlane_b32 s2, v117
	global_load_lds_dwordx4 v[4:5], off
	v_lshl_add_u64 v[4:5], v[6:7], 0, s[58:59]
	s_mov_b32 m0, s2
	s_mov_b64 s[2:3], 0xb0000
	global_load_lds_dwordx4 v[4:5], off
	v_lshl_add_u64 v[4:5], v[6:7], 0, s[2:3]
	v_readfirstlane_b32 s2, v111
	s_mov_b32 m0, s2
	s_mov_b64 s[2:3], 0xdc000
	global_load_lds_dwordx4 v[4:5], off
	v_lshl_add_u64 v[4:5], v[6:7], 0, s[2:3]
	v_readfirstlane_b32 s2, v110
	s_mov_b32 m0, s2
	s_nop 0
	global_load_lds_dwordx4 v[4:5], off

.LBB0_132:
	s_lshl_b64 s[2:3], s[88:89], 18
	v_mov_b32_e32 v4, v131
	s_add_u32 s2, s16, s2
	s_mul_i32 s42, s58, 0x30000
	s_mov_b32 s43, s89
	s_addc_u32 s3, s54, s3
	v_lshrrev_b32_e32 v0, 4, v4
	s_lshl_b64 s[42:43], s[42:43], 1
	s_waitcnt lgkmcnt(0)
	v_ashrrev_i32_e32 v2, 3, v4
	v_xor_b32_e32 v0, v0, v4
	s_add_u32 s42, s6, s42
	v_ashrrev_i32_e32 v3, 31, v2
	v_lshlrev_b32_e32 v5, 3, v0
	s_addc_u32 s43, s7, s43
	s_waitcnt vmcnt(10)
	v_lshlrev_b64 v[6:7], 11, v[2:3]
	v_and_b32_e32 v5, 56, v5
	v_lshlrev_b32_e32 v124, 4, v4
	v_lshl_add_u64 v[100:101], s[2:3], 0, v[6:7]
	v_lshl_add_u64 v[102:103], s[42:43], 0, v[6:7]
	s_and_b64 vcc, exec, s[20:21]
	v_add_u32_e32 v123, 0x1000, v124
	v_add_u32_e32 v122, 0x2000, v124
	v_add_u32_e32 v121, 0x3000, v124
	v_add_u32_e32 v120, 0x4000, v124
	v_add_u32_e32 v119, 0x5000, v124
	v_add_u32_e32 v118, 0x6000, v124
	v_add_u32_e32 v117, 0x7000, v124
	v_add_u32_e32 v111, 0x8000, v124
	v_add_u32_e32 v110, 0x9000, v124
	v_lshlrev_b32_e32 v98, 1, v5
	s_cbranch_vccnz .LBB0_134
	v_mov_b32_e32 v99, v1
	v_readfirstlane_b32 s2, v124
	v_lshl_add_u64 v[6:7], v[100:101], 0, v[98:99]
	s_mov_b32 m0, s2
	s_mov_b64 s[20:21], 0x10000
	v_readfirstlane_b32 s2, v123
	global_load_lds_dwordx4 v[6:7], off
	v_lshl_add_u64 v[10:11], v[6:7], 0, s[20:21]
	s_mov_b32 m0, s2
	s_mov_b64 s[42:43], 0x20000
	v_readfirstlane_b32 s2, v122
	global_load_lds_dwordx4 v[10:11], off
	v_lshl_add_u64 v[10:11], v[6:7], 0, s[42:43]
	s_mov_b32 m0, s2
	s_mov_b64 s[56:57], 0x30000
	v_readfirstlane_b32 s2, v121
	global_load_lds_dwordx4 v[10:11], off
	v_lshl_add_u64 v[6:7], v[6:7], 0, s[56:57]
	s_mov_b32 m0, s2
	v_readfirstlane_b32 s2, v120
	v_lshl_add_u64 v[8:9], v[102:103], 0, v[98:99]
	global_load_lds_dwordx4 v[6:7], off
	s_mov_b32 m0, s2
	v_readfirstlane_b32 s2, v119
	global_load_lds_dwordx4 v[8:9], off
	v_lshl_add_u64 v[6:7], v[8:9], 0, s[20:21]
	s_mov_b32 m0, s2
	v_readfirstlane_b32 s2, v118
	global_load_lds_dwordx4 v[6:7], off
	v_lshl_add_u64 v[6:7], v[8:9], 0, s[42:43]
	s_mov_b32 m0, s2
	v_readfirstlane_b32 s2, v117
	global_load_lds_dwordx4 v[6:7], off
	v_lshl_add_u64 v[6:7], v[8:9], 0, s[56:57]
	s_mov_b32 m0, s2
	s_mov_b64 s[2:3], 0x40000
	global_load_lds_dwordx4 v[6:7], off
	v_lshl_add_u64 v[6:7], v[8:9], 0, s[2:3]
	v_readfirstlane_b32 s2, v111
	s_mov_b32 m0, s2
	s_mov_b64 s[2:3], 0x50000
	global_load_lds_dwordx4 v[6:7], off
	v_lshl_add_u64 v[6:7], v[8:9], 0, s[2:3]
	v_readfirstlane_b32 s2, v110
	s_mov_b32 m0, s2
	s_nop 0
	global_load_lds_dwordx4 v[6:7], off

.LBB0_308:
	s_and_b64 vcc, exec, s[2:3]
	s_cbranch_vccz .LBB0_429
	v_readlane_b32 s2, v227, 0
	s_nop 0
	s_cmpk_lt_u32 s2, 0x60
	s_cbranch_scc0 .Lmixa_go
	s_mov_b32 s2, 1
	v_writelane_b32 v224, s2, 40
	s_branch .Ltail_inproj
.Lmixa_go:
	v_mov_b32_e32 v0, v131
	v_readlane_b32 s2, v226, 26
	v_readlane_b32 s3, v226, 27
	v_mov_b32_e32 v0, v131
	s_andn2_b64 vcc, exec, s[2:3]
	s_cbranch_vccnz .LBB0_429
	v_readlane_b32 s28, v224, 34
	v_readlane_b32 s29, v224, 35
	s_load_dwordx2 s[6:7], s[28:29], 0x1c0
	s_load_dwordx2 s[2:3], s[28:29], 0x70
	s_load_dwordx2 s[20:21], s[28:29], 0xa0
	s_mul_i32 s8, s38, 0x3600
	s_mul_hi_i32 s9, s38, 0x3600
	s_load_dwordx2 s[52:53], s[28:29], 0x1e0
	s_load_dwordx4 s[44:47], s[28:29], 0x1d0
	s_waitcnt lgkmcnt(0)
	s_add_u32 s8, s2, s8
	s_addc_u32 s9, s3, s9
	s_add_u32 s12, s8, 0x1200
	s_addc_u32 s13, s9, 0
	s_add_u32 s14, s8, 0x2400
	s_addc_u32 s15, s9, 0
	s_lshl_b32 s2, s38, 8
	s_ashr_i32 s3, s2, 31
	s_lshl_b64 s[2:3], s[2:3], 2
	s_add_u32 s54, s20, s2
	s_addc_u32 s55, s21, s3
	s_load_dwordx2 s[20:21], s[28:29], 0xb0
	s_load_dwordx2 s[58:59], s[28:29], 0x1a0
	s_load_dwordx4 s[48:51], s[28:29], 0x190
	v_ashrrev_i32_e32 v0, 4, v0
	v_and_b32_e32 v0, -4, v0
	v_readlane_b32 s16, v227, 0
	s_waitcnt lgkmcnt(0)
	s_add_u32 s56, s20, s2
	v_readlane_b32 s2, v224, 8
	s_addc_u32 s57, s21, s3
	s_nop 0
	v_add_u32_e32 v98, s2, v0
	s_movk_i32 s2, 0x200
	s_add_i32 s3, s16, 0xffffff00
	s_cmpk_lt_u32 s3, 0x60
	s_cselect_b32 s2, 0xffffff00, s2
	s_add_i32 s3, s16, 0xfffffea0
	s_cmpk_lt_u32 s3, 0x60
	s_cselect_b32 s2, 0xa0, s2
	v_writelane_b32 v224, s2, 41
	s_branch .LBB0_312
.LBB0_311:
	s_or_b64 exec, exec, s[2:3]
	v_readlane_b32 s2, v224, 41
	s_movk_i32 s3, 0x300
	v_writelane_b32 v224, s3, 41
	s_add_i32 s16, s16, s2
	s_lshl_b32 s2, s2, 4
	s_cmpk_gt_i32 s16, 0x2ff
	s_nop 0
	v_add_u32_e32 v98, s2, v98
	s_cbranch_scc1 .LBB0_428

.Ltail_inproj:
	v_readlane_b32 s2, v226, 28
	v_readlane_b32 s3, v226, 29
	v_mov_b32_e32 v0, v131
	s_waitcnt vmcnt(11) lgkmcnt(0)
	v_mov_b32_e32 v2, v131
	s_andn2_b64 vcc, exec, s[2:3]
	s_mov_b32 s84, 0x1ffffc0
	s_cbranch_vccnz .LBB0_623
	v_readlane_b32 s8, v224, 34
	v_readlane_b32 s9, v224, 35
	s_load_dwordx2 s[2:3], s[8:9], 0x100
	s_load_dwordx4 s[40:43], s[8:9], 0xe8
	s_load_dwordx4 s[52:55], s[8:9], 0x208
	s_load_dwordx8 s[64:71], s[8:9], 0x160
	s_ashr_i32 s39, s38, 31
	s_mul_i32 s7, s38, 0x440000
	s_load_dwordx2 s[28:29], s[8:9], 0x180
	s_load_dwordx4 s[56:59], s[8:9], 0x1b8
	s_mul_hi_i32 s6, s38, 0x440000
	s_waitcnt lgkmcnt(0)
	s_add_u32 s91, s2, s7
	v_and_b32_e32 v3, 31, v0
	v_lshrrev_b32_e32 v0, 3, v0
	s_addc_u32 s16, s3, s6
	v_and_or_b32 v121, v2, 64, v3
	s_mul_i32 s3, s38, 0xc000
	v_ashrrev_i32_e32 v2, 1, v2
	v_and_b32_e32 v120, 4, v0
	v_readlane_b32 s12, v226, 33
	s_mul_hi_i32 s2, s38, 0xc000
	s_add_u32 s60, s52, s3
	v_and_b32_e32 v118, 0xffffffc0, v2
	v_lshlrev_b32_e32 v0, 2, v120
	v_lshlrev_b32_e32 v2, 1, v120
	v_mov_b32_e32 v3, v1
	s_mov_b32 s14, s12
	v_readlane_b32 s12, v226, 30
	s_addc_u32 s61, s53, s2
	s_mul_hi_i32 s7, s38, 5
	s_mul_i32 s6, s38, 5
	v_ashrrev_i32_e32 v119, 31, v118
	v_lshl_add_u64 v[122:123], s[54:55], 0, v[0:1]
	v_or_b32_e32 v180, 0xfffff880, v120
	s_lshl_b64 s[8:9], s[38:39], 8
	v_lshl_add_u64 v[124:125], s[42:43], 0, v[0:1]
	v_lshl_add_u64 v[126:127], s[68:69], 0, v[2:3]
	s_waitcnt vmcnt(8)
	v_lshl_add_u64 v[128:129], s[40:41], 0, v[0:1]
	v_lshl_add_u64 v[134:135], s[66:67], 0, v[2:3]
	s_mov_b32 s83, 0
	s_mov_b64 s[2:3], 0
	s_mov_b32 s88, s12
	s_mov_b32 s66, 0
	s_mov_b32 s92, 0
	v_readlane_b32 s12, v224, 40
	s_nop 0
	s_cmp_eq_u32 s12, 0
	s_cbranch_scc1 .LBB0_436
	s_mov_b32 s12, 0
	v_writelane_b32 v224, s12, 40
	s_movk_i32 s83, 3
	s_movk_i32 s88, 16
	s_branch .LBB0_436

.LBB0_436:
	s_add_i32 s83, s83, 1
	v_readlane_b32 s12, v226, 0
	s_mul_i32 s15, s83, s12
	v_readlane_b32 s12, v226, 31
	s_add_i32 s15, s15, s12
	s_cmpk_lt_u32 s15, 0xc0
	s_cselect_b64 s[12:13], -1, 0
	s_cmpk_gt_u32 s15, 0xbf
	s_cselect_b64 s[68:69], -1, 0
	s_and_b64 vcc, exec, s[68:69]
	s_cbranch_vccnz .LBB0_438
	s_and_b32 s20, s15, 0xff
	s_mulk_i32 s20, 0xab
	s_lshr_b32 s92, s20, 11
	s_mul_i32 s20, s92, 12
	s_sub_i32 s15, s15, s20
	s_and_b32 s15, s15, 0xff
	v_readlane_b32 s20, v226, 32
	s_add_i32 s66, s20, s15
